# attn: waves 0-3 skip the last (fully masked for them) step of each unit
# speedup vs baseline: 1.0018x; 1.0008x over previous
.LBB0_666:
	s_waitcnt vmcnt(0) lgkmcnt(0)
	s_barrier
	s_and_b32 s36, s24, 1
	s_add_i32 s75, s24, 1
	s_cmp_ge_u32 s75, s72
	s_cbranch_scc0 .Lattn_noskip
	s_cmp_lt_u32 s67, 4
	s_cbranch_scc1 .LBB0_682
.Lattn_noskip:
	v_lshl_add_u32 v226, s36, 14, v233
	v_xor_b32_e32 v228, 32, v226
	v_xor_b32_e32 v229, 64, v226
	v_xor_b32_e32 v236, 0x60, v226
	ds_read_b128 v[82:85], v226
	ds_read_b128 v[86:89], v226 offset:4096
	ds_read_b128 v[90:93], v228
	ds_read_b128 v[94:97], v228 offset:4096
	ds_read_b128 v[98:101], v229
	ds_read_b128 v[102:105], v229 offset:4096
	ds_read_b128 v[106:109], v236
	ds_read_b128 v[110:113], v236 offset:4096
	ds_read_b128 v[114:117], v226 offset:8192
	ds_read_b128 v[118:121], v226 offset:12288
	ds_read_b128 v[122:125], v228 offset:8192
	ds_read_b128 v[126:129], v228 offset:12288
	ds_read_b128 v[130:133], v229 offset:8192
	ds_read_b128 v[134:137], v229 offset:12288
	ds_read_b128 v[138:141], v236 offset:8192
	s_cmp_ge_u32 s75, s72
	s_cbranch_scc1 .Lattn_qk_nodma
	s_mov_b32 s37, m0
	s_xor_b32 s6, s36, 1
	s_lshl_b32 s7, s6, 14
	s_add_i32 s7, s7, s69
	s_lshl_b32 s6, s6, 15
	s_add_i32 s6, s6, s70
	s_waitcnt lgkmcnt(14)
	v_mfma_f32_32x32x16_bf16 v[146:161], v[82:85], v[210:213], v[66:81]
	ds_read_b128 v[142:145], v236 offset:12288
	s_waitcnt lgkmcnt(14)
	v_mfma_f32_32x32x16_bf16 v[162:177], v[86:89], v[210:213], v[66:81]
	v_lshl_add_u64 v[82:83], v[238:239], 0, s[56:57]
	v_lshl_add_u64 v[84:85], v[240:241], 0, s[56:57]
	s_mov_b64 s[58:59], 0x40000
	v_lshl_add_u64 v[86:87], v[82:83], 0, s[58:59]
	s_mov_b32 m0, s7
	s_nop 0
	global_load_lds_dwordx4 v[86:87], off
	s_waitcnt lgkmcnt(13)
	v_mfma_f32_32x32x16_bf16 v[146:161], v[90:93], v[214:217], v[146:161]
	s_waitcnt lgkmcnt(12)
	v_mfma_f32_32x32x16_bf16 v[162:177], v[94:97], v[214:217], v[162:177]
	s_mov_b64 s[58:59], 0x20040000
	v_lshl_add_u64 v[86:87], v[84:85], 0, s[58:59]
	s_mov_b32 m0, s6
	s_nop 0
	global_load_lds_dwordx4 v[86:87], off
	s_waitcnt lgkmcnt(11)
	v_mfma_f32_32x32x16_bf16 v[146:161], v[98:101], v[218:221], v[146:161]
	s_waitcnt lgkmcnt(10)
	v_mfma_f32_32x32x16_bf16 v[162:177], v[102:105], v[218:221], v[162:177]
	s_mov_b64 s[58:59], 0x20040080
	v_lshl_add_u64 v[86:87], v[84:85], 0, s[58:59]
	s_add_i32 m0, s6, 0x2000
	s_nop 0
	global_load_lds_dwordx4 v[86:87], off
	s_waitcnt lgkmcnt(9)
	v_mfma_f32_32x32x16_bf16 v[146:161], v[106:109], v[222:225], v[146:161]
	s_waitcnt lgkmcnt(8)
	v_mfma_f32_32x32x16_bf16 v[162:177], v[110:113], v[222:225], v[162:177]
	s_mov_b64 s[58:59], 0x60000
	v_lshl_add_u64 v[86:87], v[82:83], 0, s[58:59]
	s_add_i32 m0, s7, 0x2000
	s_nop 0
	global_load_lds_dwordx4 v[86:87], off
	s_waitcnt lgkmcnt(7)
	v_mfma_f32_32x32x16_bf16 v[178:193], v[114:117], v[210:213], v[66:81]
	s_waitcnt lgkmcnt(6)
	v_mfma_f32_32x32x16_bf16 v[194:209], v[118:121], v[210:213], v[66:81]
	s_mov_b64 s[58:59], 0x20060000
	v_lshl_add_u64 v[86:87], v[84:85], 0, s[58:59]
	s_add_i32 m0, s6, 0x4000
	s_nop 0
	global_load_lds_dwordx4 v[86:87], off
	s_waitcnt lgkmcnt(5)
	v_mfma_f32_32x32x16_bf16 v[178:193], v[122:125], v[214:217], v[178:193]
	s_waitcnt lgkmcnt(4)
	v_mfma_f32_32x32x16_bf16 v[194:209], v[126:129], v[214:217], v[194:209]
	s_mov_b64 s[58:59], 0x20060080
	v_lshl_add_u64 v[86:87], v[84:85], 0, s[58:59]
	s_add_i32 m0, s6, 0x6000
	s_nop 0
	global_load_lds_dwordx4 v[86:87], off
	s_waitcnt lgkmcnt(3)
	v_mfma_f32_32x32x16_bf16 v[178:193], v[130:133], v[218:221], v[178:193]
	s_waitcnt lgkmcnt(2)
	v_mfma_f32_32x32x16_bf16 v[194:209], v[134:137], v[218:221], v[194:209]
	s_waitcnt lgkmcnt(1)
	v_mfma_f32_32x32x16_bf16 v[178:193], v[138:141], v[222:225], v[178:193]
	s_waitcnt lgkmcnt(0)
	v_mfma_f32_32x32x16_bf16 v[194:209], v[142:145], v[222:225], v[194:209]
	s_mov_b32 m0, s37
	s_branch .Lattn_qk_done
